# GEMM epilogue stores write-through sc1, barrier leader skips L2 write-back walk after phases 4 7 11 12
# speedup vs baseline: 1.0628x; 1.0071x over previous
.LBB0_260:
	s_lshl_b64 s[2:3], s[2:3], 1
	v_lshl_or_b32 v130, s1, 8, v167
	s_add_u32 s2, s62, s2
	s_addc_u32 s3, s63, s3
	v_ashrrev_i32_e32 v131, 31, v130
	v_ashrrev_i32_e32 v157, 31, v156
	v_lshl_add_u64 v[130:131], v[130:131], 1, s[2:3]
	v_lshlrev_b64 v[132:133], 11, v[156:157]
	v_lshl_add_u64 v[158:159], v[130:131], 0, v[132:133]
	v_or_b32_e32 v132, 16, v156
	v_cvt_pk_bf16_f32 v170, v126, v127
	v_cvt_pk_bf16_f32 v171, v128, v129
	v_cvt_pk_bf16_f32 v172, v122, v123
	v_cvt_pk_bf16_f32 v173, v124, v125
	v_ashrrev_i32_e32 v133, 31, v132
	global_store_dwordx4 v[158:159], v[170:173], off sc1
	v_lshlrev_b64 v[132:133], 11, v[132:133]
	v_lshl_add_u64 v[132:133], v[130:131], 0, v[132:133]
	v_cvt_pk_bf16_f32 v170, v118, v119
	v_cvt_pk_bf16_f32 v171, v120, v121
	v_cvt_pk_bf16_f32 v172, v114, v115
	v_cvt_pk_bf16_f32 v173, v116, v117
	global_store_dwordx4 v[158:159], v[170:173], off offset:256 sc1
	s_mov_b32 s1, 0x40000
	s_mov_b64 s[2:3], 0x40000
	v_cvt_pk_bf16_f32 v170, v110, v111
	v_cvt_pk_bf16_f32 v171, v112, v113
	v_cvt_pk_bf16_f32 v172, v106, v107
	v_cvt_pk_bf16_f32 v173, v108, v109
	global_store_dwordx4 v[132:133], v[170:173], off sc1
	s_nop 1
	v_cvt_pk_bf16_f32 v170, v102, v103
	v_cvt_pk_bf16_f32 v171, v104, v105
	v_cvt_pk_bf16_f32 v172, v98, v99
	v_cvt_pk_bf16_f32 v173, v100, v101
	global_store_dwordx4 v[132:133], v[170:173], off offset:256 sc1
	v_or_b32_e32 v132, 32, v156
	v_ashrrev_i32_e32 v133, 31, v132
	v_lshlrev_b64 v[132:133], 11, v[132:133]
	v_lshl_add_u64 v[132:133], v[130:131], 0, v[132:133]
	v_cvt_pk_bf16_f32 v170, v94, v95
	v_cvt_pk_bf16_f32 v171, v96, v97
	v_cvt_pk_bf16_f32 v172, v90, v91
	v_cvt_pk_bf16_f32 v173, v92, v93
	global_store_dwordx4 v[132:133], v[170:173], off sc1
	s_nop 1
	v_cvt_pk_bf16_f32 v170, v86, v87
	v_cvt_pk_bf16_f32 v171, v88, v89
	v_cvt_pk_bf16_f32 v172, v82, v83
	v_cvt_pk_bf16_f32 v173, v84, v85
	global_store_dwordx4 v[132:133], v[170:173], off offset:256 sc1
	v_or_b32_e32 v132, 48, v156
	v_ashrrev_i32_e32 v133, 31, v132
	v_lshlrev_b64 v[132:133], 11, v[132:133]
	v_lshl_add_u64 v[130:131], v[130:131], 0, v[132:133]
	v_cvt_pk_bf16_f32 v170, v78, v79
	v_cvt_pk_bf16_f32 v171, v80, v81
	v_cvt_pk_bf16_f32 v172, v74, v75
	v_cvt_pk_bf16_f32 v173, v76, v77
	global_store_dwordx4 v[130:131], v[170:173], off sc1
	v_add_co_u32_e32 v132, vcc, s1, v158
	s_nop 0
	v_cvt_pk_bf16_f32 v170, v70, v71
	v_cvt_pk_bf16_f32 v171, v72, v73
	v_cvt_pk_bf16_f32 v172, v66, v67
	v_cvt_pk_bf16_f32 v173, v68, v69
	global_store_dwordx4 v[130:131], v[170:173], off offset:256 sc1
	v_addc_co_u32_e32 v133, vcc, 0, v159, vcc
	s_nop 0
	v_cvt_pk_bf16_f32 v170, v62, v63
	v_cvt_pk_bf16_f32 v171, v64, v65
	v_cvt_pk_bf16_f32 v172, v58, v59
	v_cvt_pk_bf16_f32 v173, v60, v61
	s_mov_b32 s1, 0x48000
	v_lshl_add_u64 v[130:131], v[158:159], 0, s[2:3]
	global_store_dwordx4 v[132:133], v[170:173], off sc1
	v_add_co_u32_e32 v132, vcc, s1, v158
	s_nop 0
	v_cvt_pk_bf16_f32 v170, v54, v55
	v_cvt_pk_bf16_f32 v171, v56, v57
	v_cvt_pk_bf16_f32 v172, v46, v47
	v_cvt_pk_bf16_f32 v173, v48, v49
	global_store_dwordx4 v[130:131], v[170:173], off offset:256 sc1
	s_mov_b64 s[2:3], 0x48000
	v_addc_co_u32_e32 v133, vcc, 0, v159, vcc
	v_cvt_pk_bf16_f32 v170, v50, v51
	v_cvt_pk_bf16_f32 v171, v52, v53
	v_cvt_pk_bf16_f32 v172, v42, v43
	v_cvt_pk_bf16_f32 v173, v44, v45
	s_mov_b32 s1, 0x50000
	v_lshl_add_u64 v[130:131], v[158:159], 0, s[2:3]
	global_store_dwordx4 v[132:133], v[170:173], off sc1
	v_add_co_u32_e32 v132, vcc, s1, v158
	s_nop 0
	v_cvt_pk_bf16_f32 v170, v38, v39
	v_cvt_pk_bf16_f32 v171, v40, v41
	v_cvt_pk_bf16_f32 v172, v30, v31
	v_cvt_pk_bf16_f32 v173, v32, v33
	global_store_dwordx4 v[130:131], v[170:173], off offset:256 sc1
	s_mov_b64 s[2:3], 0x50000
	v_addc_co_u32_e32 v133, vcc, 0, v159, vcc
	v_cvt_pk_bf16_f32 v170, v34, v35
	v_cvt_pk_bf16_f32 v171, v36, v37
	v_cvt_pk_bf16_f32 v172, v26, v27
	v_cvt_pk_bf16_f32 v173, v28, v29
	s_mov_b32 s1, 0x58000
	v_lshl_add_u64 v[130:131], v[158:159], 0, s[2:3]
	global_store_dwordx4 v[132:133], v[170:173], off sc1
	s_mov_b64 s[2:3], 0x58000
	v_add_co_u32_e32 v132, vcc, s1, v158
	v_cvt_pk_bf16_f32 v170, v22, v23
	v_cvt_pk_bf16_f32 v171, v24, v25
	v_cvt_pk_bf16_f32 v172, v14, v15
	v_cvt_pk_bf16_f32 v173, v16, v17
	global_store_dwordx4 v[130:131], v[170:173], off offset:256 sc1
	v_lshl_add_u64 v[130:131], v[158:159], 0, s[2:3]
	v_addc_co_u32_e32 v133, vcc, 0, v159, vcc
	v_cvt_pk_bf16_f32 v170, v18, v19
	v_cvt_pk_bf16_f32 v171, v20, v21
	v_cvt_pk_bf16_f32 v172, v10, v11
	v_cvt_pk_bf16_f32 v173, v12, v13
	global_store_dwordx4 v[132:133], v[170:173], off sc1
	s_mov_b64 s[2:3], 0
	s_nop 0
	v_cvt_pk_bf16_f32 v170, v6, v7
	v_cvt_pk_bf16_f32 v171, v8, v9
	v_cvt_pk_bf16_f32 v172, v2, v3
	v_cvt_pk_bf16_f32 v173, v4, v5
	global_store_dwordx4 v[130:131], v[170:173], off offset:256 sc1
.LBB0_261:
	s_and_b64 vcc, exec, s[2:3]
	s_cbranch_vccz .LBB0_246
	v_lshl_add_u32 v0, s47, 7, v168
	v_ashrrev_i32_e32 v157, 31, v156
	v_lshl_add_u64 v[130:131], v[0:1], 1, s[20:21]
	v_lshlrev_b64 v[132:133], 11, v[156:157]
	v_lshl_add_u64 v[158:159], v[130:131], 0, v[132:133]
	v_pk_mul_f32 v[118:119], v[118:119], v[126:127]
	v_pk_mul_f32 v[124:125], v[116:117], v[124:125]
	v_pk_mul_f32 v[116:117], v[114:115], v[122:123]
	v_cvt_pk_bf16_f32 v114, v118, v119
	v_pk_mul_f32 v[120:121], v[120:121], v[128:129]
	v_pk_mul_f32 v[102:103], v[102:103], v[110:111]
	v_cvt_pk_bf16_f32 v115, v120, v121
	v_cvt_pk_bf16_f32 v116, v116, v117
	v_cvt_pk_bf16_f32 v117, v124, v125
	global_store_dwordx4 v[158:159], v[114:117], off sc1
	v_pk_mul_f32 v[108:109], v[100:101], v[108:109]
	v_pk_mul_f32 v[100:101], v[98:99], v[106:107]
	v_or_b32_e32 v114, 16, v156
	v_ashrrev_i32_e32 v115, 31, v114
	v_lshlrev_b64 v[114:115], 11, v[114:115]
	v_lshl_add_u64 v[114:115], v[130:131], 0, v[114:115]
	v_cvt_pk_bf16_f32 v98, v102, v103
	v_pk_mul_f32 v[104:105], v[104:105], v[112:113]
	v_pk_mul_f32 v[86:87], v[86:87], v[94:95]
	v_cvt_pk_bf16_f32 v99, v104, v105
	v_cvt_pk_bf16_f32 v100, v100, v101
	v_cvt_pk_bf16_f32 v101, v108, v109
	global_store_dwordx4 v[114:115], v[98:101], off sc1
	v_pk_mul_f32 v[92:93], v[84:85], v[92:93]
	v_pk_mul_f32 v[84:85], v[82:83], v[90:91]
	v_or_b32_e32 v98, 32, v156
	v_ashrrev_i32_e32 v99, 31, v98
	v_lshlrev_b64 v[98:99], 11, v[98:99]
	v_lshl_add_u64 v[98:99], v[130:131], 0, v[98:99]
	v_cvt_pk_bf16_f32 v82, v86, v87
	v_pk_mul_f32 v[88:89], v[88:89], v[96:97]
	v_pk_mul_f32 v[76:77], v[68:69], v[76:77]
	v_cvt_pk_bf16_f32 v83, v88, v89
	v_cvt_pk_bf16_f32 v84, v84, v85
	v_cvt_pk_bf16_f32 v85, v92, v93
	global_store_dwordx4 v[98:99], v[82:85], off sc1
	v_pk_mul_f32 v[68:69], v[66:67], v[74:75]
	v_pk_mul_f32 v[54:55], v[54:55], v[62:63]
	v_or_b32_e32 v82, 48, v156
	v_ashrrev_i32_e32 v83, 31, v82
	v_lshlrev_b64 v[82:83], 11, v[82:83]
	v_lshl_add_u64 v[82:83], v[130:131], 0, v[82:83]
	s_mov_b32 s1, 0x40000
	v_pk_mul_f32 v[72:73], v[72:73], v[80:81]
	v_pk_mul_f32 v[70:71], v[70:71], v[78:79]
	v_pk_mul_f32 v[60:61], v[48:49], v[60:61]
	v_cvt_pk_bf16_f32 v66, v70, v71
	v_cvt_pk_bf16_f32 v67, v72, v73
	v_cvt_pk_bf16_f32 v68, v68, v69
	v_cvt_pk_bf16_f32 v69, v76, v77
	global_store_dwordx4 v[82:83], v[66:69], off sc1
	v_pk_mul_f32 v[48:49], v[46:47], v[58:59]
	v_cvt_pk_bf16_f32 v46, v54, v55
	v_add_co_u32_e32 v54, vcc, s1, v158
	v_pk_mul_f32 v[38:39], v[38:39], v[50:51]
	s_nop 0
	v_addc_co_u32_e32 v55, vcc, 0, v159, vcc
	s_mov_b32 s1, 0x48000
	v_pk_mul_f32 v[56:57], v[56:57], v[64:65]
	v_pk_mul_f32 v[44:45], v[32:33], v[44:45]
	v_cvt_pk_bf16_f32 v47, v56, v57
	v_cvt_pk_bf16_f32 v48, v48, v49
	v_cvt_pk_bf16_f32 v49, v60, v61
	global_store_dwordx4 v[54:55], v[46:49], off sc1
	v_pk_mul_f32 v[32:33], v[30:31], v[42:43]
	v_cvt_pk_bf16_f32 v30, v38, v39
	v_add_co_u32_e32 v38, vcc, s1, v158
	v_pk_mul_f32 v[22:23], v[22:23], v[34:35]
	s_nop 0
	v_addc_co_u32_e32 v39, vcc, 0, v159, vcc
	s_mov_b32 s1, 0x50000
	v_pk_mul_f32 v[40:41], v[40:41], v[52:53]
	v_pk_mul_f32 v[28:29], v[16:17], v[28:29]
	v_cvt_pk_bf16_f32 v31, v40, v41
	v_cvt_pk_bf16_f32 v32, v32, v33
	v_cvt_pk_bf16_f32 v33, v44, v45
	global_store_dwordx4 v[38:39], v[30:33], off sc1
	v_pk_mul_f32 v[16:17], v[14:15], v[26:27]
	v_cvt_pk_bf16_f32 v14, v22, v23
	v_add_co_u32_e32 v22, vcc, s1, v158
	v_pk_mul_f32 v[6:7], v[6:7], v[18:19]
	s_nop 0
	v_addc_co_u32_e32 v23, vcc, 0, v159, vcc
	v_pk_mul_f32 v[24:25], v[24:25], v[36:37]
	v_pk_mul_f32 v[12:13], v[4:5], v[12:13]
	v_cvt_pk_bf16_f32 v15, v24, v25
	v_cvt_pk_bf16_f32 v16, v16, v17
	v_cvt_pk_bf16_f32 v17, v28, v29
	global_store_dwordx4 v[22:23], v[14:17], off sc1
	v_pk_mul_f32 v[4:5], v[2:3], v[10:11]
	v_cvt_pk_bf16_f32 v2, v6, v7
	v_add_co_u32_e32 v6, vcc, 0x58000, v158
	v_pk_mul_f32 v[8:9], v[8:9], v[20:21]
	s_nop 0
	v_addc_co_u32_e32 v7, vcc, 0, v159, vcc
	v_cvt_pk_bf16_f32 v3, v8, v9
	v_cvt_pk_bf16_f32 v4, v4, v5
	v_cvt_pk_bf16_f32 v5, v12, v13
	global_store_dwordx4 v[6:7], v[2:5], off sc1
	s_branch .LBB0_246

.LBB0_303:
	v_add_u32_e32 v130, s2, v141
	v_lshl_or_b32 v0, s65, 9, v167
	v_ashrrev_i32_e32 v131, 31, v130
	v_lshl_add_u64 v[132:133], v[156:157], 0, v[0:1]
	v_lshlrev_b64 v[156:157], 11, v[130:131]
	v_lshl_add_u64 v[156:157], v[132:133], 0, v[156:157]
	v_cvt_pk_bf16_f32 v126, v126, v127
	v_cvt_pk_bf16_f32 v127, v128, v129
	v_cvt_pk_bf16_f32 v128, v122, v123
	v_cvt_pk_bf16_f32 v129, v124, v125
	global_store_dwordx4 v[156:157], v[126:129], off sc1
	v_cvt_pk_bf16_f32 v114, v114, v115
	v_cvt_pk_bf16_f32 v115, v116, v117
	v_cvt_pk_bf16_f32 v116, v106, v107
	v_or_b32_e32 v106, 16, v130
	v_ashrrev_i32_e32 v107, 31, v106
	v_lshlrev_b64 v[106:107], 11, v[106:107]
	v_cvt_pk_bf16_f32 v117, v108, v109
	global_store_dwordx4 v[156:157], v[114:117], off offset:256 sc1
	s_mov_b64 s[2:3], 0x40000
	s_mov_b32 s65, s79
	v_lshl_add_u64 v[114:115], v[132:133], 0, v[106:107]
	v_cvt_pk_bf16_f32 v106, v118, v119
	v_cvt_pk_bf16_f32 v107, v120, v121
	v_cvt_pk_bf16_f32 v108, v110, v111
	v_cvt_pk_bf16_f32 v109, v112, v113
	global_store_dwordx4 v[114:115], v[106:109], off sc1
	v_cvt_pk_bf16_f32 v98, v98, v99
	v_cvt_pk_bf16_f32 v99, v100, v101
	v_cvt_pk_bf16_f32 v100, v90, v91
	v_or_b32_e32 v90, 32, v130
	v_ashrrev_i32_e32 v91, 31, v90
	v_lshlrev_b64 v[90:91], 11, v[90:91]
	v_cvt_pk_bf16_f32 v101, v92, v93
	global_store_dwordx4 v[114:115], v[98:101], off offset:256 sc1
	s_mov_b32 s68, s78
	v_readlane_b32 s78, v254, 61
	v_lshl_add_u64 v[98:99], v[132:133], 0, v[90:91]
	v_cvt_pk_bf16_f32 v90, v102, v103
	v_cvt_pk_bf16_f32 v91, v104, v105
	v_cvt_pk_bf16_f32 v92, v94, v95
	v_cvt_pk_bf16_f32 v93, v96, v97
	global_store_dwordx4 v[98:99], v[90:93], off sc1
	v_cvt_pk_bf16_f32 v82, v82, v83
	v_cvt_pk_bf16_f32 v83, v84, v85
	v_cvt_pk_bf16_f32 v84, v74, v75
	v_or_b32_e32 v74, 48, v130
	v_ashrrev_i32_e32 v75, 31, v74
	v_lshlrev_b64 v[74:75], 11, v[74:75]
	v_cvt_pk_bf16_f32 v85, v76, v77
	global_store_dwordx4 v[98:99], v[82:85], off offset:256 sc1
	s_mov_b32 s39, s77
	s_mov_b32 s42, s46
	v_lshl_add_u64 v[82:83], v[132:133], 0, v[74:75]
	v_cvt_pk_bf16_f32 v74, v86, v87
	v_cvt_pk_bf16_f32 v75, v88, v89
	v_cvt_pk_bf16_f32 v76, v78, v79
	v_cvt_pk_bf16_f32 v77, v80, v81
	global_store_dwordx4 v[82:83], v[74:77], off sc1
	v_cvt_pk_bf16_f32 v70, v70, v71
	v_cvt_pk_bf16_f32 v71, v72, v73
	v_cvt_pk_bf16_f32 v72, v66, v67
	v_lshl_add_u64 v[66:67], v[156:157], 0, s[2:3]
	s_mov_b32 s2, 0x40000
	v_cvt_pk_bf16_f32 v73, v68, v69
	global_store_dwordx4 v[82:83], v[70:73], off offset:256 sc1
	v_cvt_pk_bf16_f32 v62, v62, v63
	v_cvt_pk_bf16_f32 v63, v64, v65
	v_cvt_pk_bf16_f32 v64, v58, v59
	v_add_co_u32_e32 v58, vcc, s2, v156
	v_cvt_pk_bf16_f32 v65, v60, v61
	s_mov_b64 s[2:3], 0x48000
	s_nop 0
	v_addc_co_u32_e32 v59, vcc, 0, v157, vcc
	global_store_dwordx4 v[58:59], v[62:65], off sc1
	v_cvt_pk_bf16_f32 v50, v50, v51
	v_cvt_pk_bf16_f32 v51, v52, v53
	v_cvt_pk_bf16_f32 v52, v42, v43
	v_cvt_pk_bf16_f32 v53, v44, v45
	global_store_dwordx4 v[66:67], v[50:53], off offset:256 sc1
	v_cvt_pk_bf16_f32 v42, v54, v55
	v_cvt_pk_bf16_f32 v43, v56, v57
	v_cvt_pk_bf16_f32 v44, v46, v47
	v_cvt_pk_bf16_f32 v45, v48, v49
	s_mov_b32 s64, s76
	s_nop 0
	v_lshl_add_u64 v[50:51], v[156:157], 0, s[2:3]
	s_mov_b32 s2, 0x48000
	v_add_co_u32_e32 v46, vcc, s2, v156
	s_mov_b64 s[2:3], 0x50000
	s_nop 0
	v_addc_co_u32_e32 v47, vcc, 0, v157, vcc
	global_store_dwordx4 v[46:47], v[42:45], off sc1
	v_cvt_pk_bf16_f32 v34, v34, v35
	v_cvt_pk_bf16_f32 v35, v36, v37
	v_cvt_pk_bf16_f32 v36, v26, v27
	v_cvt_pk_bf16_f32 v37, v28, v29
	global_store_dwordx4 v[50:51], v[34:37], off offset:256 sc1
	v_cvt_pk_bf16_f32 v26, v38, v39
	v_cvt_pk_bf16_f32 v27, v40, v41
	v_cvt_pk_bf16_f32 v28, v30, v31
	v_cvt_pk_bf16_f32 v29, v32, v33
	s_mov_b64 s[98:99], s[0:1]
	s_nop 0
	v_lshl_add_u64 v[34:35], v[156:157], 0, s[2:3]
	s_mov_b32 s2, 0x50000
	v_add_co_u32_e32 v30, vcc, s2, v156
	s_mov_b64 s[2:3], 0x58000
	s_nop 0
	v_addc_co_u32_e32 v31, vcc, 0, v157, vcc
	global_store_dwordx4 v[30:31], v[26:29], off sc1
	v_cvt_pk_bf16_f32 v18, v18, v19
	v_cvt_pk_bf16_f32 v19, v20, v21
	v_cvt_pk_bf16_f32 v20, v10, v11
	v_cvt_pk_bf16_f32 v21, v12, v13
	global_store_dwordx4 v[34:35], v[18:21], off offset:256 sc1
	v_cvt_pk_bf16_f32 v10, v22, v23
	v_cvt_pk_bf16_f32 v11, v24, v25
	v_cvt_pk_bf16_f32 v12, v14, v15
	s_mov_b32 s24, s78
	v_cvt_pk_bf16_f32 v13, v16, v17
	s_nop 0
	v_lshl_add_u64 v[18:19], v[156:157], 0, s[2:3]
	s_mov_b32 s2, 0x58000
	v_add_co_u32_e32 v14, vcc, s2, v156
	s_mov_b64 s[2:3], s[20:21]
	s_nop 0
	v_addc_co_u32_e32 v15, vcc, 0, v157, vcc
	s_and_b64 vcc, exec, s[28:29]
	global_store_dwordx4 v[14:15], v[10:13], off sc1
	v_cvt_pk_bf16_f32 v6, v6, v7
	v_cvt_pk_bf16_f32 v7, v8, v9
	v_cvt_pk_bf16_f32 v8, v2, v3
	v_cvt_pk_bf16_f32 v9, v4, v5
	global_store_dwordx4 v[18:19], v[6:9], off offset:256 sc1
	v_readlane_b32 s79, v254, 62
	s_cbranch_vccnz .LBB0_322

.Lafter_437:
	s_andn2_b64 vcc, exec, s[0:1]
	s_cbranch_vccnz .LBB0_429
	v_pk_mul_f32 v[162:163], v[126:127], s[34:35] op_sel_hi:[1,0]
	v_pk_mul_f32 v[122:123], v[122:123], v[126:127]
	v_pk_mul_f32 v[126:127], v[128:129], s[34:35] op_sel_hi:[1,0]
	v_exp_f32_e32 v162, v162
	v_exp_f32_e32 v163, v163
	v_exp_f32_e32 v126, v126
	v_exp_f32_e32 v127, v127
	v_pk_mul_f32 v[124:125], v[124:125], v[128:129]
	v_pk_add_f32 v[162:163], v[162:163], 1.0 op_sel_hi:[1,0]
	v_pk_mul_f32 v[106:107], v[106:107], v[110:111]
	v_pk_add_f32 v[126:127], v[126:127], 1.0 op_sel_hi:[1,0]
	v_rcp_f32_e32 v162, v162
	v_rcp_f32_e32 v163, v163
	v_rcp_f32_e32 v126, v126
	v_rcp_f32_e32 v127, v127
	v_lshl_or_b32 v130, s40, 7, v156
	v_pk_mul_f32 v[122:123], v[122:123], v[162:163]
	v_pk_mul_f32 v[120:121], v[120:121], v[116:117]
	v_pk_mul_f32 v[124:125], v[124:125], v[126:127]
	v_cvt_pk_bf16_f32 v122, v122, v123
	v_lshl_add_u32 v158, s64, 8, v141
	v_cvt_pk_bf16_f32 v123, v124, v125
	v_pk_mul_f32 v[124:125], v[114:115], s[34:35] op_sel_hi:[1,0]
	v_pk_mul_f32 v[114:115], v[118:119], v[114:115]
	v_exp_f32_e32 v124, v124
	v_exp_f32_e32 v125, v125
	v_pk_mul_f32 v[118:119], v[110:111], s[34:35] op_sel_hi:[1,0]
	v_pk_mul_f32 v[110:111], v[112:113], s[34:35] op_sel_hi:[1,0]
	v_exp_f32_e32 v118, v118
	v_pk_add_f32 v[124:125], v[124:125], 1.0 op_sel_hi:[1,0]
	v_exp_f32_e32 v119, v119
	v_rcp_f32_e32 v124, v124
	v_rcp_f32_e32 v125, v125
	v_exp_f32_e32 v110, v110
	v_exp_f32_e32 v111, v111
	v_pk_add_f32 v[118:119], v[118:119], 1.0 op_sel_hi:[1,0]
	v_pk_mul_f32 v[114:115], v[114:115], v[124:125]
	v_rcp_f32_e32 v118, v118
	v_cvt_pk_bf16_f32 v124, v114, v115
	v_pk_mul_f32 v[114:115], v[116:117], s[34:35] op_sel_hi:[1,0]
	v_pk_add_f32 v[110:111], v[110:111], 1.0 op_sel_hi:[1,0]
	v_exp_f32_e32 v114, v114
	v_exp_f32_e32 v115, v115
	v_rcp_f32_e32 v119, v119
	v_rcp_f32_e32 v110, v110
	v_rcp_f32_e32 v111, v111
	v_pk_add_f32 v[114:115], v[114:115], 1.0 op_sel_hi:[1,0]
	v_ashrrev_i32_e32 v131, 31, v130
	v_rcp_f32_e32 v114, v114
	v_rcp_f32_e32 v115, v115
	v_mov_b64_e32 v[154:155], s[62:63]
	s_movk_i32 s20, 0x1600
	v_mad_i64_i32 v[132:133], s[2:3], v158, s20, v[154:155]
	v_pk_mul_f32 v[114:115], v[120:121], v[114:115]
	v_pk_mul_f32 v[108:109], v[108:109], v[112:113]
	v_cvt_pk_bf16_f32 v125, v114, v115
	v_lshlrev_b64 v[114:115], 1, v[130:131]
	v_lshl_add_u64 v[116:117], v[132:133], 0, v[114:115]
	v_pk_mul_f32 v[106:107], v[106:107], v[118:119]
	v_pk_mul_f32 v[108:109], v[108:109], v[110:111]
	global_store_dwordx4 v[116:117], v[122:125], off sc1
	v_cvt_pk_bf16_f32 v106, v106, v107
	v_cvt_pk_bf16_f32 v107, v108, v109
	v_pk_mul_f32 v[108:109], v[98:99], s[34:35] op_sel_hi:[1,0]
	v_pk_mul_f32 v[98:99], v[102:103], v[98:99]
	v_exp_f32_e32 v108, v108
	v_exp_f32_e32 v109, v109
	v_pk_mul_f32 v[104:105], v[104:105], v[100:101]
	v_pk_mul_f32 v[90:91], v[90:91], v[94:95]
	v_or_b32_e32 v116, 16, v158
	v_pk_add_f32 v[108:109], v[108:109], 1.0 op_sel_hi:[1,0]
	v_mad_i64_i32 v[116:117], s[2:3], v116, s20, v[154:155]
	v_rcp_f32_e32 v108, v108
	v_rcp_f32_e32 v109, v109
	v_pk_mul_f32 v[92:93], v[92:93], v[96:97]
	v_pk_mul_f32 v[88:89], v[88:89], v[84:85]
	v_pk_mul_f32 v[74:75], v[74:75], v[78:79]
	v_pk_mul_f32 v[98:99], v[98:99], v[108:109]
	v_pk_mul_f32 v[76:77], v[76:77], v[80:81]
	v_cvt_pk_bf16_f32 v108, v98, v99
	v_pk_mul_f32 v[98:99], v[100:101], s[34:35] op_sel_hi:[1,0]
	v_pk_mul_f32 v[100:101], v[94:95], s[34:35] op_sel_hi:[1,0]
	v_exp_f32_e32 v98, v98
	v_exp_f32_e32 v99, v99
	v_pk_mul_f32 v[94:95], v[96:97], s[34:35] op_sel_hi:[1,0]
	v_exp_f32_e32 v100, v100
	v_exp_f32_e32 v101, v101
	v_exp_f32_e32 v94, v94
	v_exp_f32_e32 v95, v95
	v_pk_add_f32 v[98:99], v[98:99], 1.0 op_sel_hi:[1,0]
	v_pk_add_f32 v[100:101], v[100:101], 1.0 op_sel_hi:[1,0]
	v_rcp_f32_e32 v98, v98
	v_rcp_f32_e32 v99, v99
	v_pk_add_f32 v[94:95], v[94:95], 1.0 op_sel_hi:[1,0]
	v_rcp_f32_e32 v100, v100
	v_rcp_f32_e32 v101, v101
	v_rcp_f32_e32 v94, v94
	v_rcp_f32_e32 v95, v95
	v_pk_mul_f32 v[98:99], v[104:105], v[98:99]
	v_pk_mul_f32 v[90:91], v[90:91], v[100:101]
	v_cvt_pk_bf16_f32 v109, v98, v99
	v_lshl_add_u64 v[98:99], v[116:117], 0, v[114:115]
	v_pk_mul_f32 v[92:93], v[92:93], v[94:95]
	global_store_dwordx4 v[98:99], v[106:109], off sc1
	v_cvt_pk_bf16_f32 v90, v90, v91
	v_cvt_pk_bf16_f32 v91, v92, v93
	v_pk_mul_f32 v[92:93], v[82:83], s[34:35] op_sel_hi:[1,0]
	v_pk_mul_f32 v[82:83], v[86:87], v[82:83]
	v_exp_f32_e32 v92, v92
	v_exp_f32_e32 v93, v93
	v_or_b32_e32 v98, 32, v158
	v_mad_i64_i32 v[98:99], s[2:3], v98, s20, v[154:155]
	v_pk_add_f32 v[92:93], v[92:93], 1.0 op_sel_hi:[1,0]
	v_pk_mul_f32 v[72:73], v[72:73], v[68:69]
	v_rcp_f32_e32 v92, v92
	v_rcp_f32_e32 v93, v93
	v_pk_mul_f32 v[58:59], v[58:59], v[62:63]
	v_pk_mul_f32 v[60:61], v[60:61], v[64:65]
	v_pk_mul_f32 v[56:57], v[56:57], v[52:53]
	v_pk_mul_f32 v[82:83], v[82:83], v[92:93]
	v_pk_mul_f32 v[42:43], v[42:43], v[46:47]
	v_cvt_pk_bf16_f32 v92, v82, v83
	v_pk_mul_f32 v[82:83], v[84:85], s[34:35] op_sel_hi:[1,0]
	v_pk_mul_f32 v[84:85], v[78:79], s[34:35] op_sel_hi:[1,0]
	v_exp_f32_e32 v82, v82
	v_exp_f32_e32 v83, v83
	v_pk_mul_f32 v[78:79], v[80:81], s[34:35] op_sel_hi:[1,0]
	v_exp_f32_e32 v84, v84
	v_exp_f32_e32 v85, v85
	v_exp_f32_e32 v78, v78
	v_exp_f32_e32 v79, v79
	v_pk_add_f32 v[82:83], v[82:83], 1.0 op_sel_hi:[1,0]
	v_pk_add_f32 v[84:85], v[84:85], 1.0 op_sel_hi:[1,0]
	v_rcp_f32_e32 v82, v82
	v_rcp_f32_e32 v83, v83
	v_pk_add_f32 v[78:79], v[78:79], 1.0 op_sel_hi:[1,0]
	v_rcp_f32_e32 v84, v84
	v_rcp_f32_e32 v85, v85
	v_rcp_f32_e32 v78, v78
	v_rcp_f32_e32 v79, v79
	v_pk_mul_f32 v[82:83], v[88:89], v[82:83]
	v_pk_mul_f32 v[74:75], v[74:75], v[84:85]
	v_cvt_pk_bf16_f32 v93, v82, v83
	v_lshl_add_u64 v[82:83], v[98:99], 0, v[114:115]
	v_pk_mul_f32 v[76:77], v[76:77], v[78:79]
	global_store_dwordx4 v[82:83], v[90:93], off sc1
	v_cvt_pk_bf16_f32 v74, v74, v75
	v_cvt_pk_bf16_f32 v75, v76, v77
	v_pk_mul_f32 v[76:77], v[66:67], s[34:35] op_sel_hi:[1,0]
	v_pk_mul_f32 v[66:67], v[70:71], v[66:67]
	v_exp_f32_e32 v76, v76
	v_exp_f32_e32 v77, v77
	v_or_b32_e32 v82, 48, v158
	v_mad_i64_i32 v[82:83], s[2:3], v82, s20, v[154:155]
	v_pk_add_f32 v[76:77], v[76:77], 1.0 op_sel_hi:[1,0]
	v_pk_mul_f32 v[44:45], v[44:45], v[48:49]
	v_rcp_f32_e32 v76, v76
	v_rcp_f32_e32 v77, v77
	v_pk_mul_f32 v[40:41], v[40:41], v[36:37]
	v_pk_mul_f32 v[26:27], v[26:27], v[30:31]
	v_pk_mul_f32 v[28:29], v[28:29], v[32:33]
	v_pk_mul_f32 v[66:67], v[66:67], v[76:77]
	v_pk_mul_f32 v[24:25], v[24:25], v[20:21]
	v_cvt_pk_bf16_f32 v76, v66, v67
	v_pk_mul_f32 v[66:67], v[68:69], s[34:35] op_sel_hi:[1,0]
	v_pk_mul_f32 v[68:69], v[62:63], s[34:35] op_sel_hi:[1,0]
	v_exp_f32_e32 v66, v66
	v_exp_f32_e32 v67, v67
	v_pk_mul_f32 v[62:63], v[64:65], s[34:35] op_sel_hi:[1,0]
	v_exp_f32_e32 v68, v68
	v_exp_f32_e32 v69, v69
	v_exp_f32_e32 v62, v62
	v_exp_f32_e32 v63, v63
	v_pk_add_f32 v[66:67], v[66:67], 1.0 op_sel_hi:[1,0]
	v_pk_add_f32 v[68:69], v[68:69], 1.0 op_sel_hi:[1,0]
	v_rcp_f32_e32 v66, v66
	v_rcp_f32_e32 v67, v67
	v_pk_add_f32 v[62:63], v[62:63], 1.0 op_sel_hi:[1,0]
	v_rcp_f32_e32 v68, v68
	v_rcp_f32_e32 v69, v69
	v_rcp_f32_e32 v62, v62
	v_rcp_f32_e32 v63, v63
	v_pk_mul_f32 v[66:67], v[72:73], v[66:67]
	v_pk_mul_f32 v[58:59], v[58:59], v[68:69]
	v_cvt_pk_bf16_f32 v77, v66, v67
	v_lshl_add_u64 v[66:67], v[82:83], 0, v[114:115]
	v_pk_mul_f32 v[60:61], v[60:61], v[62:63]
	global_store_dwordx4 v[66:67], v[74:77], off sc1
	v_cvt_pk_bf16_f32 v58, v58, v59
	v_cvt_pk_bf16_f32 v59, v60, v61
	v_pk_mul_f32 v[60:61], v[50:51], s[34:35] op_sel_hi:[1,0]
	v_pk_mul_f32 v[50:51], v[54:55], v[50:51]
	v_exp_f32_e32 v60, v60
	v_exp_f32_e32 v61, v61
	v_add_u32_e32 v66, 0x80, v158
	v_mad_i64_i32 v[66:67], s[2:3], v66, s20, v[154:155]
	v_pk_add_f32 v[60:61], v[60:61], 1.0 op_sel_hi:[1,0]
	v_pk_mul_f32 v[10:11], v[10:11], v[14:15]
	v_rcp_f32_e32 v60, v60
	v_rcp_f32_e32 v61, v61
	v_pk_mul_f32 v[12:13], v[12:13], v[16:17]
	v_pk_mul_f32 v[2:3], v[2:3], v[6:7]
	v_pk_mul_f32 v[4:5], v[4:5], v[8:9]
	v_pk_mul_f32 v[50:51], v[50:51], v[60:61]
	s_nop 0
	v_cvt_pk_bf16_f32 v60, v50, v51
	v_pk_mul_f32 v[50:51], v[52:53], s[34:35] op_sel_hi:[1,0]
	v_pk_mul_f32 v[52:53], v[46:47], s[34:35] op_sel_hi:[1,0]
	v_exp_f32_e32 v50, v50
	v_exp_f32_e32 v51, v51
	v_pk_mul_f32 v[46:47], v[48:49], s[34:35] op_sel_hi:[1,0]
	v_exp_f32_e32 v52, v52
	v_exp_f32_e32 v53, v53
	v_exp_f32_e32 v46, v46
	v_exp_f32_e32 v47, v47
	v_pk_add_f32 v[50:51], v[50:51], 1.0 op_sel_hi:[1,0]
	v_pk_add_f32 v[52:53], v[52:53], 1.0 op_sel_hi:[1,0]
	v_rcp_f32_e32 v50, v50
	v_rcp_f32_e32 v51, v51
	v_pk_add_f32 v[46:47], v[46:47], 1.0 op_sel_hi:[1,0]
	v_rcp_f32_e32 v52, v52
	v_rcp_f32_e32 v53, v53
	v_rcp_f32_e32 v46, v46
	v_rcp_f32_e32 v47, v47
	v_pk_mul_f32 v[50:51], v[56:57], v[50:51]
	v_pk_mul_f32 v[42:43], v[42:43], v[52:53]
	v_cvt_pk_bf16_f32 v61, v50, v51
	v_lshl_add_u64 v[50:51], v[66:67], 0, v[114:115]
	v_pk_mul_f32 v[44:45], v[44:45], v[46:47]
	global_store_dwordx4 v[50:51], v[58:61], off sc1
	v_cvt_pk_bf16_f32 v42, v42, v43
	v_cvt_pk_bf16_f32 v43, v44, v45
	v_pk_mul_f32 v[44:45], v[34:35], s[34:35] op_sel_hi:[1,0]
	v_pk_mul_f32 v[34:35], v[38:39], v[34:35]
	v_exp_f32_e32 v44, v44
	v_exp_f32_e32 v45, v45
	v_add_u32_e32 v50, 0x90, v158
	v_mad_i64_i32 v[50:51], s[2:3], v50, s20, v[154:155]
	v_pk_add_f32 v[44:45], v[44:45], 1.0 op_sel_hi:[1,0]
	s_nop 0
	v_rcp_f32_e32 v44, v44
	v_rcp_f32_e32 v45, v45
	s_nop 0
	v_pk_mul_f32 v[34:35], v[34:35], v[44:45]
	s_nop 0
	v_cvt_pk_bf16_f32 v44, v34, v35
	v_pk_mul_f32 v[34:35], v[36:37], s[34:35] op_sel_hi:[1,0]
	v_pk_mul_f32 v[36:37], v[30:31], s[34:35] op_sel_hi:[1,0]
	v_exp_f32_e32 v34, v34
	v_exp_f32_e32 v35, v35
	v_pk_mul_f32 v[30:31], v[32:33], s[34:35] op_sel_hi:[1,0]
	v_exp_f32_e32 v36, v36
	v_exp_f32_e32 v37, v37
	v_exp_f32_e32 v30, v30
	v_exp_f32_e32 v31, v31
	v_pk_add_f32 v[34:35], v[34:35], 1.0 op_sel_hi:[1,0]
	v_pk_add_f32 v[36:37], v[36:37], 1.0 op_sel_hi:[1,0]
	v_rcp_f32_e32 v34, v34
	v_rcp_f32_e32 v35, v35
	v_pk_add_f32 v[30:31], v[30:31], 1.0 op_sel_hi:[1,0]
	v_rcp_f32_e32 v36, v36
	v_rcp_f32_e32 v37, v37
	v_rcp_f32_e32 v30, v30
	v_rcp_f32_e32 v31, v31
	v_pk_mul_f32 v[34:35], v[40:41], v[34:35]
	v_pk_mul_f32 v[26:27], v[26:27], v[36:37]
	v_cvt_pk_bf16_f32 v45, v34, v35
	v_lshl_add_u64 v[34:35], v[50:51], 0, v[114:115]
	v_pk_mul_f32 v[28:29], v[28:29], v[30:31]
	global_store_dwordx4 v[34:35], v[42:45], off sc1
	v_cvt_pk_bf16_f32 v26, v26, v27
	v_cvt_pk_bf16_f32 v27, v28, v29
	v_pk_mul_f32 v[28:29], v[18:19], s[34:35] op_sel_hi:[1,0]
	v_pk_mul_f32 v[18:19], v[22:23], v[18:19]
	v_exp_f32_e32 v28, v28
	v_exp_f32_e32 v29, v29
	v_add_u32_e32 v34, 0xa0, v158
	v_mad_i64_i32 v[34:35], s[2:3], v34, s20, v[154:155]
	v_pk_add_f32 v[28:29], v[28:29], 1.0 op_sel_hi:[1,0]
	s_nop 0
	v_rcp_f32_e32 v28, v28
	v_rcp_f32_e32 v29, v29
	s_nop 0
	v_pk_mul_f32 v[18:19], v[18:19], v[28:29]
	s_nop 0
	v_cvt_pk_bf16_f32 v28, v18, v19
	v_pk_mul_f32 v[18:19], v[20:21], s[34:35] op_sel_hi:[1,0]
	v_pk_mul_f32 v[20:21], v[14:15], s[34:35] op_sel_hi:[1,0]
	v_exp_f32_e32 v18, v18
	v_exp_f32_e32 v19, v19
	v_pk_mul_f32 v[14:15], v[16:17], s[34:35] op_sel_hi:[1,0]
	v_exp_f32_e32 v20, v20
	v_exp_f32_e32 v21, v21
	v_exp_f32_e32 v14, v14
	v_exp_f32_e32 v15, v15
	v_pk_add_f32 v[18:19], v[18:19], 1.0 op_sel_hi:[1,0]
	v_pk_add_f32 v[20:21], v[20:21], 1.0 op_sel_hi:[1,0]
	v_rcp_f32_e32 v18, v18
	v_rcp_f32_e32 v19, v19
	v_pk_add_f32 v[14:15], v[14:15], 1.0 op_sel_hi:[1,0]
	v_rcp_f32_e32 v20, v20
	v_rcp_f32_e32 v21, v21
	v_rcp_f32_e32 v14, v14
	v_rcp_f32_e32 v15, v15
	v_pk_mul_f32 v[18:19], v[24:25], v[18:19]
	v_pk_mul_f32 v[10:11], v[10:11], v[20:21]
	v_cvt_pk_bf16_f32 v29, v18, v19
	v_lshl_add_u64 v[18:19], v[34:35], 0, v[114:115]
	v_pk_mul_f32 v[12:13], v[12:13], v[14:15]
	global_store_dwordx4 v[18:19], v[26:29], off sc1
	v_cvt_pk_bf16_f32 v10, v10, v11
	v_cvt_pk_bf16_f32 v11, v12, v13
	v_pk_mul_f32 v[12:13], v[6:7], s[34:35] op_sel_hi:[1,0]
	v_add_u32_e32 v18, 0xb0, v158
	v_exp_f32_e32 v12, v12
	v_exp_f32_e32 v13, v13
	v_mad_i64_i32 v[18:19], s[2:3], v18, s20, v[154:155]
	v_pk_add_f32 v[12:13], v[12:13], 1.0 op_sel_hi:[1,0]
	s_nop 0
	v_rcp_f32_e32 v12, v12
	v_rcp_f32_e32 v13, v13
	s_nop 0
	v_pk_mul_f32 v[2:3], v[2:3], v[12:13]
	s_nop 0
	v_cvt_pk_bf16_f32 v12, v2, v3
	v_pk_mul_f32 v[2:3], v[8:9], s[34:35] op_sel_hi:[1,0]
	s_nop 0
	v_exp_f32_e32 v2, v2
	v_exp_f32_e32 v3, v3
	s_nop 0
	v_pk_add_f32 v[2:3], v[2:3], 1.0 op_sel_hi:[1,0]
	s_nop 0
	v_rcp_f32_e32 v2, v2
	v_rcp_f32_e32 v3, v3
	s_nop 0
	v_pk_mul_f32 v[2:3], v[4:5], v[2:3]
	s_nop 0
	v_cvt_pk_bf16_f32 v13, v2, v3
	v_lshl_add_u64 v[2:3], v[18:19], 0, v[114:115]
	global_store_dwordx4 v[2:3], v[10:13], off sc1
	s_branch .LBB0_429

.LBB0_524:
	s_or_b64 exec, exec, s[2:3]
	v_cvt_f32_u32_e32 v5, v3
	s_waitcnt vmcnt(0)
	v_readfirstlane_b32 s2, v4
	v_sub_u32_e32 v4, 0, v3
	v_rcp_iflag_f32_e32 v5, v5
	v_add_u32_e32 v6, s2, v0
	v_mul_f32_e32 v5, 0x4f7ffffe, v5
	v_cvt_u32_f32_e32 v5, v5
	v_mul_lo_u32 v0, v4, v5
	v_mul_hi_u32 v0, v5, v0
	v_add_u32_e32 v0, v5, v0
	v_mul_hi_u32 v0, v6, v0
	v_mul_lo_u32 v4, v0, v3
	v_sub_u32_e32 v4, v6, v4
	v_add_u32_e32 v5, 1, v0
	v_cmp_ge_u32_e32 vcc, v4, v3
	s_nop 1
	v_cndmask_b32_e32 v0, v0, v5, vcc
	v_sub_u32_e32 v5, v4, v3
	v_cndmask_b32_e32 v4, v4, v5, vcc
	v_add_u32_e32 v5, 1, v0
	v_cmp_ge_u32_e32 vcc, v4, v3
	v_add_u32_e32 v4, 1, v6
	s_nop 0
	v_cndmask_b32_e32 v0, v0, v5, vcc
	v_mul_lo_u32 v5, v3, v0
	v_add_u32_e32 v3, v5, v3
	v_cmp_ne_u32_e32 vcc, v4, v3
	s_cbranch_vccnz .Lxb_poll
	s_cmp_eq_u32 s41, 9
	s_cbranch_scc1 .Lxb_nowb
	s_cmp_eq_u32 s41, 15
	s_cbranch_scc1 .Lxb_nowb
	s_cmp_eq_u32 s41, 23
	s_cbranch_scc1 .Lxb_nowb
	s_cmp_eq_u32 s41, 25
	s_cbranch_scc1 .Lxb_nowb
	buffer_wbl2 sc1
.Lxb_nowb:
	s_waitcnt vmcnt(0)
	s_add_u32 s28, s62, 0xfa92400
	s_addc_u32 s29, s63, 0
	global_atomic_add v1, v243, s[28:29]
	global_atomic_add v1, v243, s[28:29] offset:256
	global_atomic_add v1, v243, s[28:29] offset:512
	global_atomic_add v1, v243, s[28:29] offset:768
	global_atomic_add v1, v243, s[28:29] offset:1024
	global_atomic_add v1, v243, s[28:29] offset:1280
	global_atomic_add v1, v243, s[28:29] offset:1536
	global_atomic_add v1, v243, s[28:29] offset:1792
	global_atomic_add v1, v243, s[28:29] offset:2048
	global_atomic_add v1, v243, s[28:29] offset:2304
	global_atomic_add v1, v243, s[28:29] offset:2560
	global_atomic_add v1, v243, s[28:29] offset:2816
	global_atomic_add v1, v243, s[28:29] offset:3072
	global_atomic_add v1, v243, s[28:29] offset:3328
	global_atomic_add v1, v243, s[28:29] offset:3584
	global_atomic_add v1, v243, s[28:29] offset:3840
